# P0b adaLN finalize preamble: loads issued in 4 batches of 34-36 instead of 24 dependent waits
# speedup vs baseline: 1.0159x; 1.0048x over previous
.LBB0_63:
	s_or_b64 exec, exec, s[2:3]
	v_mov_b32_e32 v0, v192
	s_movk_i32 s1, 0x1000
	s_nop 0
	v_cmp_gt_i32_e32 vcc, s1, v0
	s_and_saveexec_b64 s[2:3], vcc
	s_cbranch_execz .LBB0_68
	v_readlane_b32 s8, v254, 8
	v_readlane_b32 s9, v254, 9
	v_readlane_b32 s10, v254, 10
	v_readlane_b32 s11, v254, 11
	v_lshlrev_b32_e32 v31, 2, v0
	v_lshl_add_u32 v6, v0, 2, 0
	s_sub_u32 s10, s10, 0x2000
	s_subb_u32 s11, s11, 0
	v_add_u32_e32 v32, 0x0, v31
	v_add_u32_e32 v33, 0x800, v31
	global_load_dword v40, v32, s[8:9]
	global_load_dword v60, v33, s[8:9]
	s_add_u32 s12, s78, 0x100000
	s_addc_u32 s13, s79, 0
	global_load_dword v41, v32, s[12:13]
	global_load_dword v61, v33, s[12:13]
	s_add_u32 s12, s12, 0xc000
	s_addc_u32 s13, s13, 0
	global_load_dword v42, v32, s[12:13]
	global_load_dword v62, v33, s[12:13]
	s_add_u32 s12, s12, 0xc000
	s_addc_u32 s13, s13, 0
	global_load_dword v43, v32, s[12:13]
	global_load_dword v63, v33, s[12:13]
	s_add_u32 s12, s12, 0xc000
	s_addc_u32 s13, s13, 0
	global_load_dword v44, v32, s[12:13]
	global_load_dword v64, v33, s[12:13]
	s_add_u32 s12, s12, 0xc000
	s_addc_u32 s13, s13, 0
	global_load_dword v45, v32, s[12:13]
	global_load_dword v65, v33, s[12:13]
	s_add_u32 s12, s12, 0xc000
	s_addc_u32 s13, s13, 0
	global_load_dword v46, v32, s[12:13]
	global_load_dword v66, v33, s[12:13]
	s_add_u32 s12, s12, 0xc000
	s_addc_u32 s13, s13, 0
	global_load_dword v47, v32, s[12:13]
	global_load_dword v67, v33, s[12:13]
	s_add_u32 s12, s12, 0xc000
	s_addc_u32 s13, s13, 0
	global_load_dword v48, v32, s[12:13]
	global_load_dword v68, v33, s[12:13]
	s_add_u32 s12, s12, 0xc000
	s_addc_u32 s13, s13, 0
	global_load_dword v49, v32, s[12:13]
	global_load_dword v69, v33, s[12:13]
	s_add_u32 s12, s12, 0xc000
	s_addc_u32 s13, s13, 0
	global_load_dword v50, v32, s[12:13]
	global_load_dword v70, v33, s[12:13]
	s_add_u32 s12, s12, 0xc000
	s_addc_u32 s13, s13, 0
	global_load_dword v51, v32, s[12:13]
	global_load_dword v71, v33, s[12:13]
	s_add_u32 s12, s12, 0xc000
	s_addc_u32 s13, s13, 0
	global_load_dword v52, v32, s[12:13]
	global_load_dword v72, v33, s[12:13]
	s_add_u32 s12, s12, 0xc000
	s_addc_u32 s13, s13, 0
	global_load_dword v53, v32, s[12:13]
	global_load_dword v73, v33, s[12:13]
	s_add_u32 s12, s12, 0xc000
	s_addc_u32 s13, s13, 0
	global_load_dword v54, v32, s[12:13]
	global_load_dword v74, v33, s[12:13]
	s_add_u32 s12, s12, 0xc000
	s_addc_u32 s13, s13, 0
	global_load_dword v55, v32, s[12:13]
	global_load_dword v75, v33, s[12:13]
	s_add_u32 s12, s12, 0xc000
	s_addc_u32 s13, s13, 0
	global_load_dword v56, v32, s[12:13]
	global_load_dword v76, v33, s[12:13]
	s_waitcnt vmcnt(0)
	v_add_f32_e32 v40, v40, v41
	v_add_f32_e32 v60, v60, v61
	v_add_f32_e32 v40, v40, v42
	v_add_f32_e32 v60, v60, v62
	v_add_f32_e32 v40, v40, v43
	v_add_f32_e32 v60, v60, v63
	v_add_f32_e32 v40, v40, v44
	v_add_f32_e32 v60, v60, v64
	v_add_f32_e32 v40, v40, v45
	v_add_f32_e32 v60, v60, v65
	v_add_f32_e32 v40, v40, v46
	v_add_f32_e32 v60, v60, v66
	v_add_f32_e32 v40, v40, v47
	v_add_f32_e32 v60, v60, v67
	v_add_f32_e32 v40, v40, v48
	v_add_f32_e32 v60, v60, v68
	v_add_f32_e32 v40, v40, v49
	v_add_f32_e32 v60, v60, v69
	v_add_f32_e32 v40, v40, v50
	v_add_f32_e32 v60, v60, v70
	v_add_f32_e32 v40, v40, v51
	v_add_f32_e32 v60, v60, v71
	v_add_f32_e32 v40, v40, v52
	v_add_f32_e32 v60, v60, v72
	v_add_f32_e32 v40, v40, v53
	v_add_f32_e32 v60, v60, v73
	v_add_f32_e32 v40, v40, v54
	v_add_f32_e32 v60, v60, v74
	v_add_f32_e32 v40, v40, v55
	v_add_f32_e32 v60, v60, v75
	v_add_f32_e32 v40, v40, v56
	v_add_f32_e32 v60, v60, v76
	ds_write_b32 v6, v40
	ds_write_b32 v6, v60 offset:2048
	v_add_u32_e32 v32, 0x1000, v31
	v_add_u32_e32 v33, 0x1800, v31
	global_load_dword v40, v32, s[8:9]
	global_load_dword v60, v33, s[8:9]
	s_add_u32 s12, s78, 0x100000
	s_addc_u32 s13, s79, 0
	global_load_dword v41, v32, s[12:13]
	global_load_dword v61, v33, s[12:13]
	s_add_u32 s12, s12, 0xc000
	s_addc_u32 s13, s13, 0
	global_load_dword v42, v32, s[12:13]
	global_load_dword v62, v33, s[12:13]
	s_add_u32 s12, s12, 0xc000
	s_addc_u32 s13, s13, 0
	global_load_dword v43, v32, s[12:13]
	global_load_dword v63, v33, s[12:13]
	s_add_u32 s12, s12, 0xc000
	s_addc_u32 s13, s13, 0
	global_load_dword v44, v32, s[12:13]
	global_load_dword v64, v33, s[12:13]
	s_add_u32 s12, s12, 0xc000
	s_addc_u32 s13, s13, 0
	global_load_dword v45, v32, s[12:13]
	global_load_dword v65, v33, s[12:13]
	s_add_u32 s12, s12, 0xc000
	s_addc_u32 s13, s13, 0
	global_load_dword v46, v32, s[12:13]
	global_load_dword v66, v33, s[12:13]
	s_add_u32 s12, s12, 0xc000
	s_addc_u32 s13, s13, 0
	global_load_dword v47, v32, s[12:13]
	global_load_dword v67, v33, s[12:13]
	s_add_u32 s12, s12, 0xc000
	s_addc_u32 s13, s13, 0
	global_load_dword v48, v32, s[12:13]
	global_load_dword v68, v33, s[12:13]
	s_add_u32 s12, s12, 0xc000
	s_addc_u32 s13, s13, 0
	global_load_dword v49, v32, s[12:13]
	global_load_dword v69, v33, s[12:13]
	s_add_u32 s12, s12, 0xc000
	s_addc_u32 s13, s13, 0
	global_load_dword v50, v32, s[12:13]
	global_load_dword v70, v33, s[12:13]
	s_add_u32 s12, s12, 0xc000
	s_addc_u32 s13, s13, 0
	global_load_dword v51, v32, s[12:13]
	global_load_dword v71, v33, s[12:13]
	s_add_u32 s12, s12, 0xc000
	s_addc_u32 s13, s13, 0
	global_load_dword v52, v32, s[12:13]
	global_load_dword v72, v33, s[12:13]
	s_add_u32 s12, s12, 0xc000
	s_addc_u32 s13, s13, 0
	global_load_dword v53, v32, s[12:13]
	global_load_dword v73, v33, s[12:13]
	s_add_u32 s12, s12, 0xc000
	s_addc_u32 s13, s13, 0
	global_load_dword v54, v32, s[12:13]
	global_load_dword v74, v33, s[12:13]
	s_add_u32 s12, s12, 0xc000
	s_addc_u32 s13, s13, 0
	global_load_dword v55, v32, s[12:13]
	global_load_dword v75, v33, s[12:13]
	s_add_u32 s12, s12, 0xc000
	s_addc_u32 s13, s13, 0
	global_load_dword v56, v32, s[12:13]
	global_load_dword v76, v33, s[12:13]
	s_waitcnt vmcnt(0)
	v_add_f32_e32 v40, v40, v41
	v_add_f32_e32 v60, v60, v61
	v_add_f32_e32 v40, v40, v42
	v_add_f32_e32 v60, v60, v62
	v_add_f32_e32 v40, v40, v43
	v_add_f32_e32 v60, v60, v63
	v_add_f32_e32 v40, v40, v44
	v_add_f32_e32 v60, v60, v64
	v_add_f32_e32 v40, v40, v45
	v_add_f32_e32 v60, v60, v65
	v_add_f32_e32 v40, v40, v46
	v_add_f32_e32 v60, v60, v66
	v_add_f32_e32 v40, v40, v47
	v_add_f32_e32 v60, v60, v67
	v_add_f32_e32 v40, v40, v48
	v_add_f32_e32 v60, v60, v68
	v_add_f32_e32 v40, v40, v49
	v_add_f32_e32 v60, v60, v69
	v_add_f32_e32 v40, v40, v50
	v_add_f32_e32 v60, v60, v70
	v_add_f32_e32 v40, v40, v51
	v_add_f32_e32 v60, v60, v71
	v_add_f32_e32 v40, v40, v52
	v_add_f32_e32 v60, v60, v72
	v_add_f32_e32 v40, v40, v53
	v_add_f32_e32 v60, v60, v73
	v_add_f32_e32 v40, v40, v54
	v_add_f32_e32 v60, v60, v74
	v_add_f32_e32 v40, v40, v55
	v_add_f32_e32 v60, v60, v75
	v_add_f32_e32 v40, v40, v56
	v_add_f32_e32 v60, v60, v76
	ds_write_b32 v6, v40 offset:4096
	ds_write_b32 v6, v60 offset:6144
	v_add_u32_e32 v32, 0x2000, v31
	v_add_u32_e32 v33, 0x2800, v31
	global_load_dword v40, v32, s[8:9]
	global_load_dword v60, v33, s[8:9]
	s_add_u32 s12, s78, 0x100000
	s_addc_u32 s13, s79, 0
	global_load_dword v41, v32, s[12:13]
	global_load_dword v61, v33, s[12:13]
	s_add_u32 s12, s12, 0xc000
	s_addc_u32 s13, s13, 0
	global_load_dword v42, v32, s[12:13]
	global_load_dword v62, v33, s[12:13]
	s_add_u32 s12, s12, 0xc000
	s_addc_u32 s13, s13, 0
	global_load_dword v43, v32, s[12:13]
	global_load_dword v63, v33, s[12:13]
	s_add_u32 s12, s12, 0xc000
	s_addc_u32 s13, s13, 0
	global_load_dword v44, v32, s[12:13]
	global_load_dword v64, v33, s[12:13]
	s_add_u32 s12, s12, 0xc000
	s_addc_u32 s13, s13, 0
	global_load_dword v45, v32, s[12:13]
	global_load_dword v65, v33, s[12:13]
	s_add_u32 s12, s12, 0xc000
	s_addc_u32 s13, s13, 0
	global_load_dword v46, v32, s[12:13]
	global_load_dword v66, v33, s[12:13]
	s_add_u32 s12, s12, 0xc000
	s_addc_u32 s13, s13, 0
	global_load_dword v47, v32, s[12:13]
	global_load_dword v67, v33, s[12:13]
	s_add_u32 s12, s12, 0xc000
	s_addc_u32 s13, s13, 0
	global_load_dword v48, v32, s[12:13]
	global_load_dword v68, v33, s[12:13]
	s_add_u32 s12, s12, 0xc000
	s_addc_u32 s13, s13, 0
	global_load_dword v49, v32, s[12:13]
	global_load_dword v69, v33, s[12:13]
	s_add_u32 s12, s12, 0xc000
	s_addc_u32 s13, s13, 0
	global_load_dword v50, v32, s[12:13]
	global_load_dword v70, v33, s[12:13]
	s_add_u32 s12, s12, 0xc000
	s_addc_u32 s13, s13, 0
	global_load_dword v51, v32, s[12:13]
	global_load_dword v71, v33, s[12:13]
	s_add_u32 s12, s12, 0xc000
	s_addc_u32 s13, s13, 0
	global_load_dword v52, v32, s[12:13]
	global_load_dword v72, v33, s[12:13]
	s_add_u32 s12, s12, 0xc000
	s_addc_u32 s13, s13, 0
	global_load_dword v53, v32, s[12:13]
	global_load_dword v73, v33, s[12:13]
	s_add_u32 s12, s12, 0xc000
	s_addc_u32 s13, s13, 0
	global_load_dword v54, v32, s[12:13]
	global_load_dword v74, v33, s[12:13]
	s_add_u32 s12, s12, 0xc000
	s_addc_u32 s13, s13, 0
	global_load_dword v55, v32, s[12:13]
	global_load_dword v75, v33, s[12:13]
	s_add_u32 s12, s12, 0xc000
	s_addc_u32 s13, s13, 0
	global_load_dword v56, v32, s[12:13]
	global_load_dword v76, v33, s[12:13]
	global_load_dword v57, v32, s[10:11]
	global_load_dword v77, v33, s[10:11]
	s_waitcnt vmcnt(0)
	v_add_f32_e32 v40, v40, v41
	v_add_f32_e32 v60, v60, v61
	v_add_f32_e32 v40, v40, v42
	v_add_f32_e32 v60, v60, v62
	v_add_f32_e32 v40, v40, v43
	v_add_f32_e32 v60, v60, v63
	v_add_f32_e32 v40, v40, v44
	v_add_f32_e32 v60, v60, v64
	v_add_f32_e32 v40, v40, v45
	v_add_f32_e32 v60, v60, v65
	v_add_f32_e32 v40, v40, v46
	v_add_f32_e32 v60, v60, v66
	v_add_f32_e32 v40, v40, v47
	v_add_f32_e32 v60, v60, v67
	v_add_f32_e32 v40, v40, v48
	v_add_f32_e32 v60, v60, v68
	v_add_f32_e32 v40, v40, v49
	v_add_f32_e32 v60, v60, v69
	v_add_f32_e32 v40, v40, v50
	v_add_f32_e32 v60, v60, v70
	v_add_f32_e32 v40, v40, v51
	v_add_f32_e32 v60, v60, v71
	v_add_f32_e32 v40, v40, v52
	v_add_f32_e32 v60, v60, v72
	v_add_f32_e32 v40, v40, v53
	v_add_f32_e32 v60, v60, v73
	v_add_f32_e32 v40, v40, v54
	v_add_f32_e32 v60, v60, v74
	v_add_f32_e32 v40, v40, v55
	v_add_f32_e32 v60, v60, v75
	v_add_f32_e32 v40, v40, v56
	v_add_f32_e32 v60, v60, v76
	v_add_f32_e32 v40, 1.0, v40
	v_add_f32_e32 v60, 1.0, v60
	v_mul_f32_e32 v40, v40, v57
	v_mul_f32_e32 v60, v60, v77
	ds_write_b32 v6, v40 offset:8192
	ds_write_b32 v6, v60 offset:10240
	v_add_u32_e32 v32, 0x3000, v31
	v_add_u32_e32 v33, 0x3800, v31
	global_load_dword v40, v32, s[8:9]
	global_load_dword v60, v33, s[8:9]
	s_add_u32 s12, s78, 0x100000
	s_addc_u32 s13, s79, 0
	global_load_dword v41, v32, s[12:13]
	global_load_dword v61, v33, s[12:13]
	s_add_u32 s12, s12, 0xc000
	s_addc_u32 s13, s13, 0
	global_load_dword v42, v32, s[12:13]
	global_load_dword v62, v33, s[12:13]
	s_add_u32 s12, s12, 0xc000
	s_addc_u32 s13, s13, 0
	global_load_dword v43, v32, s[12:13]
	global_load_dword v63, v33, s[12:13]
	s_add_u32 s12, s12, 0xc000
	s_addc_u32 s13, s13, 0
	global_load_dword v44, v32, s[12:13]
	global_load_dword v64, v33, s[12:13]
	s_add_u32 s12, s12, 0xc000
	s_addc_u32 s13, s13, 0
	global_load_dword v45, v32, s[12:13]
	global_load_dword v65, v33, s[12:13]
	s_add_u32 s12, s12, 0xc000
	s_addc_u32 s13, s13, 0
	global_load_dword v46, v32, s[12:13]
	global_load_dword v66, v33, s[12:13]
	s_add_u32 s12, s12, 0xc000
	s_addc_u32 s13, s13, 0
	global_load_dword v47, v32, s[12:13]
	global_load_dword v67, v33, s[12:13]
	s_add_u32 s12, s12, 0xc000
	s_addc_u32 s13, s13, 0
	global_load_dword v48, v32, s[12:13]
	global_load_dword v68, v33, s[12:13]
	s_add_u32 s12, s12, 0xc000
	s_addc_u32 s13, s13, 0
	global_load_dword v49, v32, s[12:13]
	global_load_dword v69, v33, s[12:13]
	s_add_u32 s12, s12, 0xc000
	s_addc_u32 s13, s13, 0
	global_load_dword v50, v32, s[12:13]
	global_load_dword v70, v33, s[12:13]
	s_add_u32 s12, s12, 0xc000
	s_addc_u32 s13, s13, 0
	global_load_dword v51, v32, s[12:13]
	global_load_dword v71, v33, s[12:13]
	s_add_u32 s12, s12, 0xc000
	s_addc_u32 s13, s13, 0
	global_load_dword v52, v32, s[12:13]
	global_load_dword v72, v33, s[12:13]
	s_add_u32 s12, s12, 0xc000
	s_addc_u32 s13, s13, 0
	global_load_dword v53, v32, s[12:13]
	global_load_dword v73, v33, s[12:13]
	s_add_u32 s12, s12, 0xc000
	s_addc_u32 s13, s13, 0
	global_load_dword v54, v32, s[12:13]
	global_load_dword v74, v33, s[12:13]
	s_add_u32 s12, s12, 0xc000
	s_addc_u32 s13, s13, 0
	global_load_dword v55, v32, s[12:13]
	global_load_dword v75, v33, s[12:13]
	s_add_u32 s12, s12, 0xc000
	s_addc_u32 s13, s13, 0
	global_load_dword v56, v32, s[12:13]
	global_load_dword v76, v33, s[12:13]
	global_load_dword v57, v32, s[10:11]
	global_load_dword v77, v33, s[10:11]
	s_waitcnt vmcnt(0)
	v_add_f32_e32 v40, v40, v41
	v_add_f32_e32 v60, v60, v61
	v_add_f32_e32 v40, v40, v42
	v_add_f32_e32 v60, v60, v62
	v_add_f32_e32 v40, v40, v43
	v_add_f32_e32 v60, v60, v63
	v_add_f32_e32 v40, v40, v44
	v_add_f32_e32 v60, v60, v64
	v_add_f32_e32 v40, v40, v45
	v_add_f32_e32 v60, v60, v65
	v_add_f32_e32 v40, v40, v46
	v_add_f32_e32 v60, v60, v66
	v_add_f32_e32 v40, v40, v47
	v_add_f32_e32 v60, v60, v67
	v_add_f32_e32 v40, v40, v48
	v_add_f32_e32 v60, v60, v68
	v_add_f32_e32 v40, v40, v49
	v_add_f32_e32 v60, v60, v69
	v_add_f32_e32 v40, v40, v50
	v_add_f32_e32 v60, v60, v70
	v_add_f32_e32 v40, v40, v51
	v_add_f32_e32 v60, v60, v71
	v_add_f32_e32 v40, v40, v52
	v_add_f32_e32 v60, v60, v72
	v_add_f32_e32 v40, v40, v53
	v_add_f32_e32 v60, v60, v73
	v_add_f32_e32 v40, v40, v54
	v_add_f32_e32 v60, v60, v74
	v_add_f32_e32 v40, v40, v55
	v_add_f32_e32 v60, v60, v75
	v_add_f32_e32 v40, v40, v56
	v_add_f32_e32 v60, v60, v76
	v_add_f32_e32 v40, 1.0, v40
	v_add_f32_e32 v60, 1.0, v60
	v_mul_f32_e32 v40, v40, v57
	v_mul_f32_e32 v60, v60, v77
	ds_write_b32 v6, v40 offset:12288
	ds_write_b32 v6, v60 offset:14336
